# v69 + P1 KBIAS rows and P2 attention items made batch-aligned with the XCDs (permutation of the same work), seams 1 and 2 XCD-local too (global seams left: 0,5,7)
# speedup vs baseline: 1.0274x; 1.0168x over previous
; #define LAS __attribute__((address_space(3)))
; __global__ void __launch_bounds__(NWAVES * 64, 2) mk_fwd(Params P) {
;     ...
;         if (bx < BATCH * 8) {
;             const float* src = LOGF + (size_t)bx * SEQ + tid * 8; float* dst = KBIAS + (size_t)bx * SEQ + tid * 8;
;             const f32x4 a = *(const f32x4*)src, b = *(const f32x4*)(src + 4);
;             float p[8]; p[0] = a[0]; p[1] = p[0] + a[1]; p[2] = p[1] + a[2]; p[3] = p[2] + a[3]; p[4] = p[3] + b[0]; p[5] = p[4] + b[1]; p[6] = p[5] + b[2]; p[7] = p[6] + b[3];
;             float inc = p[7];
; #pragma unroll
;             for (int o = 1; o < 64; o <<= 1) { const float t = __shfl_up(inc, o); if (lane >= o) inc += t; }
;             LAS float* wt = (LAS float*)lds;
;             if (lane == 63) wt[wave] = inc;
;             __syncthreads();
.LBB0_211:
	s_cmp_lt_i32 s74, 2
	s_cselect_b64 s[2:3], -1, 0
	s_and_b64 s[42:43], s[2:3], s[0:1]
	s_andn2_b64 vcc, exec, s[42:43]
	s_cbranch_vccnz .LBB0_460
	s_and_b32 s2, s93, 0xffffffc0
	s_ashr_i32 s89, s88, 31
	s_cmp_gt_i32 s88, 63
	v_and_b32_e32 v11, 64, v212
	v_mov_b32_e32 v10, v212
	s_cbranch_scc1 .LBB0_224
	s_and_b32 s0, s88, 7
	s_lshl_b32 s0, s0, 3
	s_lshr_b32 s1, s88, 3
	s_or_b32 s0, s0, s1
	s_lshl_b32 s0, s0, 14
	s_mov_b32 s1, 0
	s_add_u32 s0, s72, s0
	v_add_lshl_u32 v4, v10, s2, 3
	s_addc_u32 s1, s73, s1
	v_ashrrev_i32_e32 v5, 31, v4
	v_lshl_add_u64 v[6:7], v[4:5], 2, s[0:1]
	v_add_co_u32_e32 v0, vcc, 0x1be00000, v6
	s_mov_b64 s[0:1], 0x1be00000
	s_nop 0
	v_addc_co_u32_e32 v1, vcc, 0, v7, vcc
	global_load_dwordx4 v[0:3], v[0:1], off
	v_lshl_add_u64 v[6:7], v[6:7], 0, s[0:1]
	global_load_dwordx4 v[12:15], v[6:7], off offset:16
	v_add_u32_e32 v6, -1, v212
	v_cmp_lt_i32_e32 vcc, v6, v11
	s_waitcnt vmcnt(1)
	v_add_f32_e32 v1, v0, v1
	v_add_f32_e32 v8, v2, v1
	v_cndmask_b32_e32 v6, v6, v212, vcc
	v_add_f32_e32 v9, v3, v8
	v_lshlrev_b32_e32 v16, 2, v6
	s_waitcnt vmcnt(0)
	v_add_f32_e32 v6, v12, v9
	v_add_f32_e32 v7, v13, v6
	v_add_f32_e32 v2, v14, v7
	v_add_f32_e32 v3, v15, v2
	ds_bpermute_b32 v12, v16, v3
	v_add_u32_e32 v13, -2, v212
	v_cmp_lt_i32_e32 vcc, v13, v11
	v_add_u32_e32 v14, -4, v212
	s_waitcnt lgkmcnt(0)
	v_add_f32_e32 v12, v3, v12
	v_cndmask_b32_e32 v13, v13, v212, vcc
	v_cmp_gt_i32_e32 vcc, 1, v10
	v_lshlrev_b32_e32 v13, 2, v13
	s_nop 0
	v_cndmask_b32_e32 v12, v12, v3, vcc
	ds_bpermute_b32 v13, v13, v12
	v_cmp_lt_i32_e32 vcc, v14, v11
	s_waitcnt lgkmcnt(0)
	v_add_f32_e32 v13, v12, v13
	v_cndmask_b32_e32 v14, v14, v212, vcc
	v_cmp_gt_i32_e32 vcc, 2, v10
	v_lshlrev_b32_e32 v14, 2, v14
	s_nop 0
	v_cndmask_b32_e32 v12, v13, v12, vcc
	ds_bpermute_b32 v13, v14, v12
	v_add_u32_e32 v14, -8, v212
	v_cmp_lt_i32_e32 vcc, v14, v11
	s_waitcnt lgkmcnt(0)
	v_add_f32_e32 v13, v12, v13
	v_cndmask_b32_e32 v14, v14, v212, vcc
	v_cmp_gt_i32_e32 vcc, 4, v10
	v_lshlrev_b32_e32 v14, 2, v14
	s_nop 0
	v_cndmask_b32_e32 v12, v13, v12, vcc
	ds_bpermute_b32 v13, v14, v12
	v_add_u32_e32 v14, -16, v212
	v_cmp_lt_i32_e32 vcc, v14, v11
	s_waitcnt lgkmcnt(0)
	v_add_f32_e32 v13, v12, v13
	v_cndmask_b32_e32 v14, v14, v212, vcc
	v_cmp_gt_i32_e32 vcc, 8, v10
	v_lshlrev_b32_e32 v14, 2, v14
	s_nop 0
	v_cndmask_b32_e32 v12, v13, v12, vcc
	ds_bpermute_b32 v13, v14, v12
	v_subrev_u32_e32 v14, 32, v212
	v_cmp_lt_i32_e32 vcc, v14, v11
	s_waitcnt lgkmcnt(0)
	v_add_f32_e32 v13, v12, v13
	v_cndmask_b32_e32 v14, v14, v212, vcc
	v_cmp_gt_i32_e32 vcc, 16, v10
	v_lshlrev_b32_e32 v14, 2, v14
	s_nop 0
	v_cndmask_b32_e32 v12, v13, v12, vcc
	ds_bpermute_b32 v13, v14, v12
	v_cmp_eq_u32_e32 vcc, 63, v10
	s_waitcnt lgkmcnt(0)
	v_add_f32_e32 v13, v12, v13
	s_and_saveexec_b64 s[0:1], vcc
	s_lshl_b32 s3, s87, 2
	s_add_i32 s3, s3, 0
	v_mov_b32_e32 v14, s3
	ds_write_b32 v14, v13
	s_or_b64 exec, exec, s[0:1]
	v_cmp_gt_i32_e32 vcc, 32, v10
	s_waitcnt lgkmcnt(0)
	s_barrier
	v_cndmask_b32_e32 v10, v13, v12, vcc
	s_andn2_b64 vcc, exec, s[16:17]
	v_sub_f32_e32 v10, v10, v3
	s_cbranch_vccnz .LBB0_223
	s_add_i32 s0, s87, -1
	s_cmp_lt_u32 s0, 7
	s_cbranch_scc1 .LBB0_220
	s_and_b32 s0, s87, 0x3fffff8
	s_mov_b32 s1, 0
	s_mov_b32 s3, 0

; __global__ void __launch_bounds__(NWAVES * 64, 2) mk_fwd(Params P) {
;     ...
;             float pre = inc - p[7];
;             for (int w = 0; w < wave; ++w) pre += wt[w];
;             const float c = -1.4426950408889634f;
;             *(f32x4*)dst = (f32x4){(pre + p[0]) * c, (pre + p[1]) * c, (pre + p[2]) * c, (pre + p[3]) * c};
;             *(f32x4*)(dst + 4) = (f32x4){(pre + p[4]) * c, (pre + p[5]) * c, (pre + p[6]) * c, (pre + p[7]) * c};
;             __syncthreads();
.LBB0_223:
	s_and_b32 s0, s88, 7
	s_lshl_b32 s0, s0, 3
	s_lshr_b32 s1, s88, 3
	s_or_b32 s0, s0, s1
	s_lshl_b32 s0, s0, 14
	s_mov_b32 s1, 0
	s_add_u32 s0, s72, s0
	s_addc_u32 s1, s73, s1
	v_lshl_add_u64 v[4:5], v[4:5], 2, s[0:1]
	s_mov_b64 s[0:1], 0x1bf00000
	v_lshl_add_u64 v[16:17], v[4:5], 0, s[0:1]
	v_pk_add_f32 v[0:1], v[0:1], v[10:11] op_sel_hi:[1,0]
	v_pk_add_f32 v[8:9], v[8:9], v[10:11] op_sel_hi:[1,0]
	s_mov_b32 s0, 0xbfb8aa3b
	v_pk_mul_f32 v[14:15], v[8:9], s[0:1] op_sel_hi:[1,0]
	v_pk_mul_f32 v[12:13], v[0:1], s[0:1] op_sel_hi:[1,0]
	s_mov_b32 s1, 0x1bf00000
	v_add_co_u32_e32 v0, vcc, s1, v4
	v_pk_add_f32 v[2:3], v[2:3], v[10:11] op_sel_hi:[1,0]
	s_nop 0
	v_addc_co_u32_e32 v1, vcc, 0, v5, vcc
	global_store_dwordx4 v[0:1], v[12:15], off
	v_pk_add_f32 v[0:1], v[6:7], v[10:11] op_sel_hi:[1,0]
	v_pk_mul_f32 v[2:3], v[2:3], s[0:1] op_sel_hi:[1,0]
	v_pk_mul_f32 v[0:1], v[0:1], s[0:1] op_sel_hi:[1,0]
	global_store_dwordx4 v[16:17], v[0:3], off offset:16
	s_barrier

; __device__ __forceinline__ unsigned xb_ld(unsigned* p)              { return __hip_atomic_load(p, __ATOMIC_RELAXED, __HIP_MEMORY_SCOPE_AGENT); }
; __device__ __forceinline__ unsigned xb_add(unsigned* p, unsigned v) { return __hip_atomic_fetch_add(p, v, __ATOMIC_RELAXED, __HIP_MEMORY_SCOPE_AGENT); }
; #define XB_SPIN(cond, bar) do { unsigned _sp = 0; while (cond) { __builtin_amdgcn_s_sleep(1); \
;     if ((++_sp & 255u) == 0u) { if (xb_ld(&(bar)[XB_TMO])) break; if (_sp > XB_SPIN_CAP) { atomicAdd(&(bar)[XB_TMO], 1u); break; } } } } while (0)
; __device__ __forceinline__ void xcd_barrier(const XcdBarrier& b, bool leader) {
;     asm volatile("s_waitcnt vmcnt(0)" ::: "memory");
;     __syncthreads();
;     if (leader) {
;         unsigned* bar = b.bar;
;         __builtin_amdgcn_s_waitcnt(0);
;         unsigned nloc = b.st[0], nx = b.st[1];
;         if (nloc == 0u) { xcd_barrier_complete(bar, b.x, nloc, nx); b.st[0] = nloc; b.st[1] = nx; }
;         const unsigned old = xb_add(&bar[XB_XSUB(b.x)], 1u);
;         const unsigned gen = old / nloc;
;         if (old + 1u == (gen + 1u) * nloc) {
;             __builtin_amdgcn_fence(__ATOMIC_RELEASE, "agent");
;             asm volatile("s_waitcnt vmcnt(0)" ::: "memory");
;             const unsigned og = xb_add(&bar[XB_TOP], 1u);
;             const unsigned tg = og / nx;
;             if (og + 1u == (tg + 1u) * nx) xb_add(&bar[XB_TOPGEN], 1u);
;             else XB_SPIN(xb_ld(&bar[XB_TOPGEN]) == tg, bar);
;             __builtin_amdgcn_fence(__ATOMIC_ACQUIRE, "agent");
;             xb_add(&bar[XB_XGEN(b.x)], 1u);
;             asm volatile("s_waitcnt vmcnt(0)" ::: "memory");
;         } else {
;             XB_SPIN(xb_ld(&bar[XB_XGEN(b.x)]) == gen, bar);
;             __builtin_amdgcn_fence(__ATOMIC_ACQUIRE, "agent");
;             asm volatile("s_waitcnt vmcnt(0)" ::: "memory");
;         }
;     }
;     __syncthreads();
; }
.LBB0_460:
	s_cmp_gt_i32 s75, 2
	s_cselect_b64 s[0:1], -1, 0
	s_and_b64 s[2:3], s[42:43], s[0:1]
	s_andn2_b64 vcc, exec, s[2:3]
	s_cbranch_vccnz .LBB0_512
	v_readlane_b32 s2, v254, 4
	v_readlane_b32 s3, v254, 5
	s_and_b64 vcc, exec, s[2:3]
	s_mov_b64 s[6:7], 0
	s_cbranch_vccnz .LBB0_463
	v_mov_b32_e32 v0, v212
	s_nop 0
	v_cmp_eq_u32_e32 vcc, 0, v0
	s_and_b64 s[6:7], vcc, exec
.LBB0_463:
	s_waitcnt vmcnt(0)
	s_waitcnt lgkmcnt(0)
	s_barrier
	s_and_saveexec_b64 s[4:5], s[6:7]
	s_cbranch_execz .LBB0_511
	v_readlane_b32 s8, v254, 2
	v_readlane_b32 s9, v254, 3
	s_and_b32 s2, s88, 7
	s_lshl_b32 s2, s2, 8
	s_add_u32 s2, s8, s2
	s_addc_u32 s3, s9, 0
	v_mov_b32_e32 v0, 0
	v_mov_b32_e32 v1, 1
	v_mov_b32_e32 v5, 0x1400
	global_load_dwordx4 v[6:9], v0, s[8:9] offset:768 sc1
	global_load_dwordx4 v[10:13], v0, s[8:9] offset:784 sc1
	global_atomic_add v3, v5, v1, s[2:3] offset:128 sc0
	s_waitcnt vmcnt(0)
	v_add_u32_e32 v14, -1, v6
	v_and_b32_e32 v2, v14, v6
	v_add_u32_e32 v14, -1, v7
	v_and_or_b32 v2, v14, v7, v2
	v_add_u32_e32 v14, -1, v8
	v_and_or_b32 v2, v14, v8, v2
	v_add_u32_e32 v14, -1, v9
	v_and_or_b32 v2, v14, v9, v2
	v_add_u32_e32 v14, -1, v10
	v_and_or_b32 v2, v14, v10, v2
	v_add_u32_e32 v14, -1, v11
	v_and_or_b32 v2, v14, v11, v2
	v_add_u32_e32 v14, -1, v12
	v_and_or_b32 v2, v14, v12, v2
	v_add_u32_e32 v14, -1, v13
	v_and_or_b32 v2, v14, v13, v2
	v_cmp_ne_u32_e32 vcc, 0, v2
	s_cbranch_vccnz .Lmy_glob_k1
	v_and_b32_e32 v4, 0xffffffe0, v3
	v_add_u32_e32 v4, 32, v4
	v_add_u32_e32 v3, 1, v3
	v_cmp_eq_u32_e32 vcc, v3, v4
	s_cbranch_vccnz .Lmy_done_k1
	s_mov_b32 s10, 0

; __device__ __forceinline__ unsigned xb_ld(unsigned* p)              { return __hip_atomic_load(p, __ATOMIC_RELAXED, __HIP_MEMORY_SCOPE_AGENT); }
; __device__ __forceinline__ unsigned xb_add(unsigned* p, unsigned v) { return __hip_atomic_fetch_add(p, v, __ATOMIC_RELAXED, __HIP_MEMORY_SCOPE_AGENT); }
; #define XB_SPIN(cond, bar) do { unsigned _sp = 0; while (cond) { __builtin_amdgcn_s_sleep(1); \
;     if ((++_sp & 255u) == 0u) { if (xb_ld(&(bar)[XB_TMO])) break; if (_sp > XB_SPIN_CAP) { atomicAdd(&(bar)[XB_TMO], 1u); break; } } } } while (0)
; __device__ __forceinline__ void xcd_barrier(const XcdBarrier& b, bool leader) {
;     asm volatile("s_waitcnt vmcnt(0)" ::: "memory");
;     __syncthreads();
;     if (leader) {
;         unsigned* bar = b.bar;
;         __builtin_amdgcn_s_waitcnt(0);
;         unsigned nloc = b.st[0], nx = b.st[1];
;         if (nloc == 0u) { xcd_barrier_complete(bar, b.x, nloc, nx); b.st[0] = nloc; b.st[1] = nx; }
;         const unsigned old = xb_add(&bar[XB_XSUB(b.x)], 1u);
;         const unsigned gen = old / nloc;
;         if (old + 1u == (gen + 1u) * nloc) {
;             __builtin_amdgcn_fence(__ATOMIC_RELEASE, "agent");
;             asm volatile("s_waitcnt vmcnt(0)" ::: "memory");
;             const unsigned og = xb_add(&bar[XB_TOP], 1u);
;             const unsigned tg = og / nx;
;             if (og + 1u == (tg + 1u) * nx) xb_add(&bar[XB_TOPGEN], 1u);
;             else XB_SPIN(xb_ld(&bar[XB_TOPGEN]) == tg, bar);
;             __builtin_amdgcn_fence(__ATOMIC_ACQUIRE, "agent");
;             xb_add(&bar[XB_XGEN(b.x)], 1u);
;             asm volatile("s_waitcnt vmcnt(0)" ::: "memory");
;         } else {
;             XB_SPIN(xb_ld(&bar[XB_XGEN(b.x)]) == gen, bar);
;             __builtin_amdgcn_fence(__ATOMIC_ACQUIRE, "agent");
;             asm volatile("s_waitcnt vmcnt(0)" ::: "memory");
;         }
;     }
;     __syncthreads();
; }
.Lmy_glob_k1:
	s_add_i32 s2, 0, 0x20400
	v_mov_b32_e32 v0, s2
	s_waitcnt vmcnt(0) expcnt(0) lgkmcnt(0)
	ds_read_b32 v2, v0
	s_add_i32 s2, 0, 0x20404
	v_mov_b32_e32 v0, s2
	ds_read_b32 v0, v0
	s_waitcnt lgkmcnt(1)
	v_cmp_ne_u32_e32 vcc, 0, v2
	s_cbranch_vccnz .LBB0_479
	v_readlane_b32 s6, v254, 0
	v_readlane_b32 s7, v254, 1
	s_load_dwordx2 s[2:3], s[6:7], 0x4
	s_add_u32 s6, s72, 0x310200
	s_addc_u32 s7, s73, 0
	s_add_u32 s8, s72, 0x310400
	s_addc_u32 s9, s73, 0
	s_add_u32 s10, s72, 0x310500
	s_addc_u32 s11, s73, 0
	s_add_u32 s12, s72, 0x310600
	s_addc_u32 s13, s73, 0
	s_add_u32 s14, s72, 0x310700
	s_addc_u32 s15, s73, 0
	s_add_u32 s16, s72, 0x310800
	s_addc_u32 s17, s73, 0
	s_add_u32 s18, s72, 0x310900
	s_addc_u32 s19, s73, 0
	s_add_u32 s22, s72, 0x310a00
	s_addc_u32 s23, s73, 0
	s_add_u32 s24, s72, 0x310b00
	s_addc_u32 s25, s73, 0
	s_add_u32 s26, s72, 0x310c00
	s_addc_u32 s27, s73, 0
	s_add_u32 s28, s72, 0x310d00
	s_addc_u32 s29, s73, 0
	s_add_u32 s30, s72, 0x310e00
	s_addc_u32 s31, s73, 0
	s_add_u32 s34, s72, 0x310f00
	s_addc_u32 s35, s73, 0
	s_add_u32 s42, s72, 0x311000
	s_addc_u32 s43, s73, 0
	s_add_u32 s44, s72, 0x311100
	s_addc_u32 s45, s73, 0
	s_add_u32 s46, s72, 0x311200
	s_addc_u32 s47, s73, 0
	s_waitcnt lgkmcnt(0)
	s_mul_i32 s2, s2, s82
	s_add_u32 s48, s72, 0x311300
	s_mul_i32 s2, s2, s3
	s_addc_u32 s49, s73, 0
	s_mov_b32 s3, 1
	v_mov_b32_e32 v16, 0
	s_branch .LBB0_467

; __global__ void __launch_bounds__(NWAVES * 64, 2) mk_fwd(Params P) {
;     ...
;         for (int p = vcu; p < 1024; p += G) {
;             const int pp = p & 511, bh = pp >> 3, s = pp & 7, b = bh >> 3, hm = bh & 7;
;     ...
;             if (rep_ == 1 && !((MK_REP_ATT) & (p < 512 ? 1 : 2))) continue;
;     ...
;             for (int hh = 0; hh < 2; ++hh) {
;                 const int qb = hh ? s : 15 - s;
.LBB0_516:
	s_bfe_u32 s32, s95, 0x30005
	s_lshl_b32 s32, s32, 6
	s_bfe_u32 s33, s95, 0x10008
	s_lshl_b32 s33, s33, 5
	s_or_b32 s32, s32, s33
	s_and_b32 s33, s95, 0x21f
	s_or_b32 s32, s32, s33
	s_and_b32 s76, s32, 7
	s_bfe_u32 s0, s32, 0x30006
	s_bfe_u32 s1, s32, 0x30003
	s_xor_b32 s92, s76, 15
	s_cmpk_gt_i32 s32, 0x1ff
	s_cselect_b64 s[46:47], -1, 0
	s_lshl_b32 s2, s1, 3
	s_lshl_b32 s4, s0, 7
	s_or_b32 s2, s4, s2
	v_readlane_b32 s4, v254, 47
	s_add_u32 s48, s4, s2
	v_readlane_b32 s4, v254, 48
	s_addc_u32 s49, s4, 0
	s_lshl_b32 s4, s1, 14
	s_lshl_b32 s5, s0, 17
	s_or_b32 s4, s5, s4
	v_readlane_b32 s5, v254, 49
	s_add_u32 s50, s5, s4
	v_readlane_b32 s4, v254, 50
	s_addc_u32 s51, s4, 0
	s_lshl_b32 s1, s1, 7
	v_readlane_b32 s4, v254, 51
	s_add_u32 s52, s4, s1
	v_readlane_b32 s4, v254, 52
	s_addc_u32 s53, s4, 0
	v_readlane_b32 s4, v254, 53
	s_add_u32 s20, s4, s1
	v_readlane_b32 s4, v254, 54
	s_addc_u32 s21, s4, 0
	v_readlane_b32 s4, v254, 55
	s_add_u32 s79, s4, s1
	v_readlane_b32 s4, v254, 56
	s_addc_u32 s36, s4, 0
	v_readlane_b32 s4, v254, 57
	s_add_u32 s54, s4, s1
	v_readlane_b32 s4, v254, 58
	s_addc_u32 s55, s4, 0
	s_lshl_b32 s37, s0, 12
	v_readlane_b32 s4, v254, 60
	s_add_u32 s56, s4, s2
	v_readlane_b32 s2, v254, 61
	s_addc_u32 s57, s2, 0
	v_readlane_b32 s2, v254, 62
	s_add_u32 s38, s2, s1
	v_readlane_b32 s2, v254, 63
	s_addc_u32 s39, s2, 0
	v_readlane_b32 s2, v255, 0
	s_add_u32 s1, s2, s1
	v_readlane_b32 s2, v255, 1
	s_addc_u32 s2, s2, 0
	s_lshl_b32 s4, s32, 4
	s_and_b32 s4, s4, 0x300
	v_readlane_b32 s5, v255, 2
	s_add_u32 s5, s5, s4
	v_readlane_b32 s6, v255, 3
	s_addc_u32 s6, s6, 0
	s_lshl_b32 s7, s32, 7
	s_and_b32 s7, s7, 0x400
	v_readlane_b32 s8, v255, 4
	s_add_u32 s7, s8, s7
	v_readlane_b32 s8, v255, 5
	s_addc_u32 s8, s8, 0
	s_add_u32 s40, s7, s4
	s_addc_u32 s41, s8, 0
	s_mul_i32 s0, s0, 0x1800000
	s_add_u32 s58, s1, s0
	s_addc_u32 s59, s2, 0
	s_add_u32 s60, s5, s0
	s_addc_u32 s61, s6, 0
	s_mov_b64 s[84:85], -1
	s_branch .LBB0_519

; __device__ __forceinline__ unsigned xb_ld(unsigned* p)              { return __hip_atomic_load(p, __ATOMIC_RELAXED, __HIP_MEMORY_SCOPE_AGENT); }
; __device__ __forceinline__ unsigned xb_add(unsigned* p, unsigned v) { return __hip_atomic_fetch_add(p, v, __ATOMIC_RELAXED, __HIP_MEMORY_SCOPE_AGENT); }
; #define XB_SPIN(cond, bar) do { unsigned _sp = 0; while (cond) { __builtin_amdgcn_s_sleep(1); \
;     if ((++_sp & 255u) == 0u) { if (xb_ld(&(bar)[XB_TMO])) break; if (_sp > XB_SPIN_CAP) { atomicAdd(&(bar)[XB_TMO], 1u); break; } } } } while (0)
; __device__ __forceinline__ void xcd_barrier(const XcdBarrier& b, bool leader) {
;     asm volatile("s_waitcnt vmcnt(0)" ::: "memory");
;     __syncthreads();
;     if (leader) {
;         unsigned* bar = b.bar;
;         __builtin_amdgcn_s_waitcnt(0);
;         unsigned nloc = b.st[0], nx = b.st[1];
;         if (nloc == 0u) { xcd_barrier_complete(bar, b.x, nloc, nx); b.st[0] = nloc; b.st[1] = nx; }
;         const unsigned old = xb_add(&bar[XB_XSUB(b.x)], 1u);
;         const unsigned gen = old / nloc;
;         if (old + 1u == (gen + 1u) * nloc) {
;             __builtin_amdgcn_fence(__ATOMIC_RELEASE, "agent");
;             asm volatile("s_waitcnt vmcnt(0)" ::: "memory");
;             const unsigned og = xb_add(&bar[XB_TOP], 1u);
;             const unsigned tg = og / nx;
;             if (og + 1u == (tg + 1u) * nx) xb_add(&bar[XB_TOPGEN], 1u);
;             else XB_SPIN(xb_ld(&bar[XB_TOPGEN]) == tg, bar);
;             __builtin_amdgcn_fence(__ATOMIC_ACQUIRE, "agent");
;             xb_add(&bar[XB_XGEN(b.x)], 1u);
;             asm volatile("s_waitcnt vmcnt(0)" ::: "memory");
;         } else {
;             XB_SPIN(xb_ld(&bar[XB_XGEN(b.x)]) == gen, bar);
;             __builtin_amdgcn_fence(__ATOMIC_ACQUIRE, "agent");
;             asm volatile("s_waitcnt vmcnt(0)" ::: "memory");
;         }
;     }
;     __syncthreads();
; }
.LBB0_747:
	s_cmp_gt_i32 s75, 3
	v_readlane_b32 s2, v254, 40
	s_cselect_b64 s[0:1], -1, 0
	v_readlane_b32 s3, v254, 41
	s_and_b64 s[2:3], s[2:3], s[0:1]
	s_andn2_b64 vcc, exec, s[2:3]
	s_cbranch_vccnz .LBB0_799
	v_readlane_b32 s2, v254, 4
	v_readlane_b32 s3, v254, 5
	s_and_b64 vcc, exec, s[2:3]
	s_mov_b64 s[6:7], 0
	s_cbranch_vccnz .LBB0_750
	v_mov_b32_e32 v0, v212
	s_nop 0
	v_cmp_eq_u32_e32 vcc, 0, v0
	s_and_b64 s[6:7], vcc, exec
.LBB0_750:
	s_waitcnt vmcnt(0)
	s_waitcnt lgkmcnt(0)
	s_barrier
	s_and_saveexec_b64 s[4:5], s[6:7]
	s_cbranch_execz .LBB0_798
	v_readlane_b32 s8, v254, 2
	v_readlane_b32 s9, v254, 3
	s_and_b32 s2, s88, 7
	s_lshl_b32 s2, s2, 8
	s_add_u32 s2, s8, s2
	s_addc_u32 s3, s9, 0
	v_mov_b32_e32 v0, 0
	v_mov_b32_e32 v1, 1
	v_mov_b32_e32 v5, 0x1400
	global_load_dwordx4 v[6:9], v0, s[8:9] offset:768 sc1
	global_load_dwordx4 v[10:13], v0, s[8:9] offset:784 sc1
	global_atomic_add v3, v5, v1, s[2:3] offset:128 sc0
	s_waitcnt vmcnt(0)
	v_add_u32_e32 v14, -1, v6
	v_and_b32_e32 v2, v14, v6
	v_add_u32_e32 v14, -1, v7
	v_and_or_b32 v2, v14, v7, v2
	v_add_u32_e32 v14, -1, v8
	v_and_or_b32 v2, v14, v8, v2
	v_add_u32_e32 v14, -1, v9
	v_and_or_b32 v2, v14, v9, v2
	v_add_u32_e32 v14, -1, v10
	v_and_or_b32 v2, v14, v10, v2
	v_add_u32_e32 v14, -1, v11
	v_and_or_b32 v2, v14, v11, v2
	v_add_u32_e32 v14, -1, v12
	v_and_or_b32 v2, v14, v12, v2
	v_add_u32_e32 v14, -1, v13
	v_and_or_b32 v2, v14, v13, v2
	v_cmp_ne_u32_e32 vcc, 0, v2
	s_cbranch_vccnz .Lmy_glob_k2
	v_and_b32_e32 v4, 0xffffffe0, v3
	v_add_u32_e32 v4, 32, v4
	v_add_u32_e32 v3, 1, v3
	v_cmp_eq_u32_e32 vcc, v3, v4
	s_cbranch_vccnz .Lmy_done_k2
	s_mov_b32 s10, 0
